# phase-0 GEMV item: the 12 c/c_ctx staging loads issued together; cache-conversion item de-serialized
# speedup vs baseline: 1.0809x; 1.0061x over previous
.LBB0_11:
	s_cmpk_gt_i32 s58, 0x17f
	s_mov_b64 s[0:1], -1
	s_cbranch_scc0 .LBB0_105
	s_cmpk_gt_u32 s58, 0xd63
	s_cbranch_scc0 .LBB0_70
	s_cmpk_lt_u32 s58, 0xde4
	s_cbranch_scc1 .LBB0_63
	s_waitcnt lgkmcnt(0)
	s_sub_i32 s8, s58, 0xde4
	s_lshr_b32 s9, s8, 6
	s_and_b32 s8, s8, 63
	s_lshl_b32 s8, s8, 11
	v_readlane_b32 s6, v242, 3
	v_readlane_b32 s7, v242, 4
	s_bitcmp1_b32 s9, 0
	s_cselect_b64 s[0:1], s[86:87], s[84:85]
	s_cselect_b64 s[4:5], s[90:91], s[88:89]
	s_cmp_lt_u32 s9, 2
	s_cselect_b64 s[4:5], s[0:1], s[4:5]
	s_lshl_b32 s0, s9, 18
	s_add_u32 s0, s0, 0x2ff4000
	s_add_u32 s6, s6, s0
	s_addc_u32 s7, s7, 0
	v_add_u32_e32 v2, s8, v137
	v_and_b32_e32 v3, 0xffff8000, v2
	s_bitcmp1_b32 s9, 0
	s_cbranch_scc1 .Lp0c_vt
	v_and_b32_e32 v80, 0x3fc0, v2
	v_lshl_or_b32 v3, v80, 1, v3
	v_bfe_u32 v80, v2, 14, 1
	v_lshl_or_b32 v3, v80, 6, v3
	v_and_or_b32 v3, v2, 63, v3
	v_lshlrev_b32_e32 v3, 2, v3
	global_load_dword v4, v3, s[4:5]
	v_add_u32_e32 v3, 0x800, v3
	global_load_dword v5, v3, s[4:5]
	v_add_u32_e32 v3, 0x800, v3
	global_load_dword v6, v3, s[4:5]
	v_add_u32_e32 v3, 0x800, v3
	global_load_dword v7, v3, s[4:5]
	v_add_u32_e32 v3, 0x800, v3
	global_load_dword v8, v3, s[4:5]
	v_add_u32_e32 v3, 0x800, v3
	global_load_dword v9, v3, s[4:5]
	v_add_u32_e32 v3, 0x800, v3
	global_load_dword v10, v3, s[4:5]
	v_add_u32_e32 v3, 0x800, v3
	global_load_dword v11, v3, s[4:5]
	s_branch .Lp0c_st
.Lp0c_vt:
	v_and_b32_e32 v80, 0xff, v2
	v_lshl_or_b32 v3, v80, 7, v3
	v_bfe_u32 v80, v2, 8, 7
	v_or_b32_e32 v3, v3, v80
	v_lshlrev_b32_e32 v3, 2, v3
	global_load_dword v4, v3, s[4:5] offset:0
	global_load_dword v5, v3, s[4:5] offset:4
	global_load_dword v6, v3, s[4:5] offset:8
	global_load_dword v7, v3, s[4:5] offset:12
	global_load_dword v8, v3, s[4:5] offset:16
	global_load_dword v9, v3, s[4:5] offset:20
	global_load_dword v10, v3, s[4:5] offset:24
	global_load_dword v11, v3, s[4:5] offset:28
.Lp0c_st:
	v_lshlrev_b32_e32 v2, 1, v2
	s_waitcnt vmcnt(7)
	v_cvt_pk_bf16_f32 v4, v4, v4
	global_store_short v2, v4, s[6:7] offset:0
	s_waitcnt vmcnt(6)
	v_cvt_pk_bf16_f32 v5, v5, v5
	global_store_short v2, v5, s[6:7] offset:512
	s_waitcnt vmcnt(5)
	v_cvt_pk_bf16_f32 v6, v6, v6
	global_store_short v2, v6, s[6:7] offset:1024
	s_waitcnt vmcnt(4)
	v_cvt_pk_bf16_f32 v7, v7, v7
	global_store_short v2, v7, s[6:7] offset:1536
	s_waitcnt vmcnt(3)
	v_cvt_pk_bf16_f32 v8, v8, v8
	global_store_short v2, v8, s[6:7] offset:2048
	s_waitcnt vmcnt(2)
	v_cvt_pk_bf16_f32 v9, v9, v9
	global_store_short v2, v9, s[6:7] offset:2560
	s_waitcnt vmcnt(1)
	v_cvt_pk_bf16_f32 v10, v10, v10
	global_store_short v2, v10, s[6:7] offset:3072
	s_waitcnt vmcnt(0)
	v_cvt_pk_bf16_f32 v11, v11, v11
	global_store_short v2, v11, s[6:7] offset:3584
	s_mov_b64 s[0:1], 0

.LBB0_105:
	s_andn2_b64 vcc, exec, s[0:1]
	s_cbranch_vccnz .LBB0_10
	v_mov_b32_e32 v99, v137
	s_mov_b64 s[0:1], exec
	v_lshlrev_b32_e32 v2, 2, v137
	v_add_u32_e32 v3, 0x1000, v2
	s_waitcnt lgkmcnt(0)
	global_load_dword v4, v2, s[64:65]
	global_load_dword v5, v2, s[64:65] offset:1024
	global_load_dword v6, v2, s[64:65] offset:2048
	global_load_dword v7, v2, s[64:65] offset:3072
	global_load_dword v8, v2, s[94:95]
	global_load_dword v9, v2, s[94:95] offset:1024
	global_load_dword v10, v2, s[94:95] offset:2048
	global_load_dword v11, v2, s[94:95] offset:3072
	global_load_dword v12, v3, s[94:95]
	global_load_dword v13, v3, s[94:95] offset:1024
	global_load_dword v14, v3, s[94:95] offset:2048
	global_load_dword v15, v3, s[94:95] offset:3072
	s_waitcnt vmcnt(11)
	v_mul_f32_e32 v16, 0xbfb8aa3b, v4
	v_exp_f32_e32 v16, v16
	s_nop 0
	v_add_f32_e32 v16, 1.0, v16
	v_rcp_f32_e32 v16, v16
	s_nop 0
	v_mul_f32_e32 v16, v4, v16
	ds_write_b32 v2, v16
	s_waitcnt vmcnt(10)
	v_mul_f32_e32 v17, 0xbfb8aa3b, v5
	v_exp_f32_e32 v17, v17
	s_nop 0
	v_add_f32_e32 v17, 1.0, v17
	v_rcp_f32_e32 v17, v17
	s_nop 0
	v_mul_f32_e32 v17, v5, v17
	ds_write_b32 v2, v17 offset:1024
	s_waitcnt vmcnt(9)
	v_mul_f32_e32 v18, 0xbfb8aa3b, v6
	v_exp_f32_e32 v18, v18
	s_nop 0
	v_add_f32_e32 v18, 1.0, v18
	v_rcp_f32_e32 v18, v18
	s_nop 0
	v_mul_f32_e32 v18, v6, v18
	ds_write_b32 v2, v18 offset:2048
	s_waitcnt vmcnt(8)
	v_mul_f32_e32 v19, 0xbfb8aa3b, v7
	v_exp_f32_e32 v19, v19
	s_nop 0
	v_add_f32_e32 v19, 1.0, v19
	v_rcp_f32_e32 v19, v19
	s_nop 0
	v_mul_f32_e32 v19, v7, v19
	ds_write_b32 v2, v19 offset:3072
	s_waitcnt vmcnt(7)
	v_mul_f32_e32 v16, 0xbfb8aa3b, v8
	v_exp_f32_e32 v16, v16
	s_nop 0
	v_add_f32_e32 v16, 1.0, v16
	v_rcp_f32_e32 v16, v16
	s_nop 0
	v_mul_f32_e32 v16, v8, v16
	ds_write_b32 v2, v16 offset:4096
	s_waitcnt vmcnt(6)
	v_mul_f32_e32 v17, 0xbfb8aa3b, v9
	v_exp_f32_e32 v17, v17
	s_nop 0
	v_add_f32_e32 v17, 1.0, v17
	v_rcp_f32_e32 v17, v17
	s_nop 0
	v_mul_f32_e32 v17, v9, v17
	ds_write_b32 v2, v17 offset:5120
	s_waitcnt vmcnt(5)
	v_mul_f32_e32 v18, 0xbfb8aa3b, v10
	v_exp_f32_e32 v18, v18
	s_nop 0
	v_add_f32_e32 v18, 1.0, v18
	v_rcp_f32_e32 v18, v18
	s_nop 0
	v_mul_f32_e32 v18, v10, v18
	ds_write_b32 v2, v18 offset:6144
	s_waitcnt vmcnt(4)
	v_mul_f32_e32 v19, 0xbfb8aa3b, v11
	v_exp_f32_e32 v19, v19
	s_nop 0
	v_add_f32_e32 v19, 1.0, v19
	v_rcp_f32_e32 v19, v19
	s_nop 0
	v_mul_f32_e32 v19, v11, v19
	ds_write_b32 v2, v19 offset:7168
	s_waitcnt vmcnt(3)
	v_mul_f32_e32 v16, 0xbfb8aa3b, v12
	v_exp_f32_e32 v16, v16
	s_nop 0
	v_add_f32_e32 v16, 1.0, v16
	v_rcp_f32_e32 v16, v16
	s_nop 0
	v_mul_f32_e32 v16, v12, v16
	ds_write_b32 v2, v16 offset:8192
	s_waitcnt vmcnt(2)
	v_mul_f32_e32 v17, 0xbfb8aa3b, v13
	v_exp_f32_e32 v17, v17
	s_nop 0
	v_add_f32_e32 v17, 1.0, v17
	v_rcp_f32_e32 v17, v17
	s_nop 0
	v_mul_f32_e32 v17, v13, v17
	ds_write_b32 v2, v17 offset:9216
	s_waitcnt vmcnt(1)
	v_mul_f32_e32 v18, 0xbfb8aa3b, v14
	v_exp_f32_e32 v18, v18
	s_nop 0
	v_add_f32_e32 v18, 1.0, v18
	v_rcp_f32_e32 v18, v18
	s_nop 0
	v_mul_f32_e32 v18, v14, v18
	ds_write_b32 v2, v18 offset:10240
	s_waitcnt vmcnt(0)
	v_mul_f32_e32 v19, 0xbfb8aa3b, v15
	v_exp_f32_e32 v19, v19
	s_nop 0
	v_add_f32_e32 v19, 1.0, v19
	v_rcp_f32_e32 v19, v19
	s_nop 0
	v_mul_f32_e32 v19, v15, v19
	ds_write_b32 v2, v19 offset:11264

.LBB0_114:
	v_lshl_add_u64 v[88:89], v[84:85], 0, s[38:39]
	ds_read_b128 v[62:65], v107
	ds_read_b128 v[58:61], v107 offset:16
	ds_read_b128 v[54:57], v107 offset:32
	ds_read_b128 v[50:53], v107 offset:48
	ds_read_b128 v[2:5], v107 offset:4096
	ds_read_b128 v[6:9], v107 offset:4112
	ds_read_b128 v[18:21], v107 offset:8192
	ds_read_b128 v[14:17], v107 offset:8208
	ds_read_b128 v[10:13], v107 offset:8224
	ds_read_b128 v[22:25], v107 offset:4128
	ds_read_b128 v[26:29], v107 offset:4144
	ds_read_b128 v[30:33], v107 offset:8240
	ds_read_b128 v[66:69], v107 offset:64
	ds_read_b128 v[34:37], v107 offset:4160
	ds_read_b128 v[70:73], v107 offset:80
	ds_read_b128 v[38:41], v107 offset:4176
	ds_read_b128 v[74:77], v107 offset:96
	ds_read_b128 v[42:45], v107 offset:4192
	ds_read_b128 v[176:179], v107 offset:112
	ds_read_b128 v[46:49], v107 offset:4208
	global_load_dword v166, v[88:89], off nt
	s_mov_b32 s0, 0xc000
	s_mov_b32 s4, 0x12000
	s_mov_b32 s6, 0x18000
	v_add_co_u32_e64 v110, s[0:1], s0, v88
	v_add_co_u32_e64 v112, s[4:5], s4, v88
	v_add_co_u32_e64 v114, s[6:7], s6, v88
	v_add_co_u32_e32 v108, vcc, s33, v88
	v_addc_co_u32_e64 v111, s[0:1], 0, v89, s[0:1]
	v_addc_co_u32_e64 v113, s[4:5], 0, v89, s[4:5]
	v_addc_co_u32_e64 v115, s[6:7], 0, v89, s[6:7]
	s_mov_b32 s8, 0x1e000
	s_mov_b32 s10, 0x24000
	s_mov_b32 s12, 0x2a000
	s_mov_b32 s14, 0x30000
	s_mov_b32 s16, 0x36000
	s_mov_b32 s18, 0x3c000
	s_mov_b32 s20, 0x42000
	s_mov_b32 s22, 0x48000
	s_mov_b32 s24, 0x4e000
	s_mov_b32 s26, 0x54000
	s_mov_b32 s28, 0x5a000
	s_mov_b32 s30, 0x60000
	s_mov_b32 s34, 0x66000
	s_mov_b32 s36, 0x6c000
	s_mov_b32 s40, 0x72000
	s_mov_b32 s42, 0x78000
	s_mov_b32 s44, 0x7e000
	s_mov_b32 s46, 0x84000
	s_mov_b32 s48, 0x8a000
	s_mov_b32 s50, 0x90000
	s_mov_b32 s52, 0x96000
	s_mov_b32 s54, 0x9c000
	s_mov_b32 s56, 0xa2000
	v_addc_co_u32_e32 v109, vcc, 0, v89, vcc
	s_mov_b32 s97, 0xa8000
	s_mov_b32 s0, 0xae000
	s_mov_b32 s4, 0xb4000
	s_mov_b32 s6, 0xba000
	v_add_co_u32_e64 v116, s[8:9], s8, v88
	v_add_co_u32_e64 v118, s[10:11], s10, v88
	v_add_co_u32_e64 v120, s[12:13], s12, v88
	v_add_co_u32_e64 v122, s[14:15], s14, v88
	v_add_co_u32_e64 v124, s[16:17], s16, v88
	v_add_co_u32_e64 v126, s[18:19], s18, v88
	v_add_co_u32_e64 v128, s[20:21], s20, v88
	v_add_co_u32_e64 v146, s[22:23], s22, v88
	v_add_co_u32_e64 v148, s[24:25], s24, v88
	v_add_co_u32_e64 v150, s[26:27], s26, v88
	v_add_co_u32_e64 v152, s[28:29], s28, v88
	v_add_co_u32_e64 v154, s[30:31], s30, v88
	v_add_co_u32_e64 v156, s[34:35], s34, v88
	v_add_co_u32_e64 v158, s[36:37], s36, v88
	v_add_co_u32_e64 v160, s[40:41], s40, v88
	v_add_co_u32_e64 v162, s[42:43], s42, v88
	v_add_co_u32_e64 v164, s[44:45], s44, v88
	v_add_co_u32_e64 v172, s[46:47], s46, v88
	v_add_co_u32_e64 v174, s[48:49], s48, v88
	v_add_co_u32_e64 v180, s[50:51], s50, v88
	v_add_co_u32_e64 v182, s[52:53], s52, v88
	v_add_co_u32_e64 v184, s[54:55], s54, v88
	v_add_co_u32_e64 v186, s[56:57], s56, v88
	v_add_co_u32_e32 v188, vcc, s97, v88
	v_add_co_u32_e64 v190, s[0:1], s0, v88
	v_add_co_u32_e64 v192, s[4:5], s4, v88
	v_add_co_u32_e64 v88, s[6:7], s6, v88
	v_addc_co_u32_e64 v117, s[8:9], 0, v89, s[8:9]
	v_addc_co_u32_e64 v119, s[8:9], 0, v89, s[10:11]
	v_addc_co_u32_e64 v121, s[8:9], 0, v89, s[12:13]
	v_addc_co_u32_e64 v123, s[8:9], 0, v89, s[14:15]
	v_addc_co_u32_e64 v125, s[8:9], 0, v89, s[16:17]
	v_addc_co_u32_e64 v127, s[8:9], 0, v89, s[18:19]
	v_addc_co_u32_e64 v129, s[8:9], 0, v89, s[20:21]
	v_addc_co_u32_e64 v147, s[8:9], 0, v89, s[22:23]
	v_addc_co_u32_e64 v149, s[8:9], 0, v89, s[24:25]
	v_addc_co_u32_e64 v151, s[8:9], 0, v89, s[26:27]
	v_addc_co_u32_e64 v153, s[8:9], 0, v89, s[28:29]
	v_addc_co_u32_e64 v155, s[8:9], 0, v89, s[30:31]
	v_addc_co_u32_e64 v157, s[8:9], 0, v89, s[34:35]
	v_addc_co_u32_e64 v159, s[8:9], 0, v89, s[36:37]
	v_addc_co_u32_e64 v161, s[8:9], 0, v89, s[40:41]
	v_addc_co_u32_e64 v163, s[8:9], 0, v89, s[42:43]
	v_addc_co_u32_e64 v165, s[8:9], 0, v89, s[44:45]
	v_addc_co_u32_e64 v173, s[8:9], 0, v89, s[46:47]
	v_addc_co_u32_e64 v175, s[8:9], 0, v89, s[48:49]
	v_addc_co_u32_e64 v181, s[8:9], 0, v89, s[50:51]
	v_addc_co_u32_e64 v183, s[8:9], 0, v89, s[52:53]
	v_addc_co_u32_e64 v185, s[8:9], 0, v89, s[54:55]
	v_addc_co_u32_e64 v187, s[8:9], 0, v89, s[56:57]
	v_addc_co_u32_e32 v189, vcc, 0, v89, vcc
	v_addc_co_u32_e64 v191, vcc, 0, v89, s[0:1]
	v_addc_co_u32_e64 v193, vcc, 0, v89, s[4:5]
	v_addc_co_u32_e64 v89, vcc, 0, v89, s[6:7]
	global_load_dword v170, v[108:109], off nt
	global_load_dword v168, v[110:111], off nt
	global_load_dword v144, v[112:113], off nt
	global_load_dword v142, v[114:115], off nt
	global_load_dword v140, v[116:117], off nt
	global_load_dword v138, v[118:119], off nt
	global_load_dword v136, v[120:121], off nt
	global_load_dword v134, v[122:123], off nt
	global_load_dword v132, v[124:125], off nt
	global_load_dword v130, v[126:127], off nt
	s_nop 0
	global_load_dword v128, v[128:129], off nt
	s_nop 0
	global_load_dword v126, v[146:147], off nt
	global_load_dword v124, v[148:149], off nt
	global_load_dword v122, v[150:151], off nt
	global_load_dword v120, v[152:153], off nt
	global_load_dword v118, v[154:155], off nt
	global_load_dword v116, v[156:157], off nt
	global_load_dword v114, v[158:159], off nt
	global_load_dword v112, v[160:161], off nt
	global_load_dword v110, v[162:163], off nt
	global_load_dword v108, v[164:165], off nt
	global_load_dword v106, v[172:173], off nt
	global_load_dword v104, v[174:175], off nt
	global_load_dword v102, v[180:181], off nt
	global_load_dword v100, v[182:183], off nt
	global_load_dword v98, v[184:185], off nt
	global_load_dword v96, v[186:187], off nt
	global_load_dword v94, v[188:189], off nt
	global_load_dword v92, v[190:191], off nt
	global_load_dword v90, v[192:193], off nt
	s_nop 0
	global_load_dword v88, v[88:89], off nt
	s_waitcnt lgkmcnt(14)
	v_mov_b32_e32 v174, v62
	v_mov_b32_e32 v175, v2
	v_mov_b32_e32 v2, v63
	v_mov_b32_e32 v160, v54
	s_waitcnt lgkmcnt(10)
	v_mov_b32_e32 v161, v22
	v_mov_b32_e32 v22, v55
	s_waitcnt vmcnt(31)
	v_pk_fma_f32 v[54:55], v[166:167], v[174:175], v[86:87] op_sel_hi:[0,1,1]
	v_fmac_f32_e32 v105, v166, v18
	v_mov_b32_e32 v172, v64
	v_mov_b32_e32 v173, v4
	v_mov_b32_e32 v4, v65
	v_mov_b32_e32 v164, v58
	v_mov_b32_e32 v165, v6
	v_mov_b32_e32 v6, v59
	v_mov_b32_e32 v162, v60
	v_mov_b32_e32 v163, v8
	v_mov_b32_e32 v8, v61
	v_mov_b32_e32 v158, v56
	v_mov_b32_e32 v159, v24
	v_mov_b32_e32 v24, v57
	v_mov_b32_e32 v156, v50
	s_waitcnt lgkmcnt(9)
	v_mov_b32_e32 v157, v26
	ds_read_b128 v[62:65], v107 offset:8256
	v_mov_b32_e32 v26, v51
	v_mov_b32_e32 v154, v52
	v_mov_b32_e32 v155, v28
	v_mov_b32_e32 v28, v53
	s_waitcnt lgkmcnt(8)
	v_mov_b32_e32 v152, v66
	s_waitcnt lgkmcnt(7)
	v_mov_b32_e32 v153, v34
	ds_read_b128 v[50:53], v107 offset:8272
	v_mov_b32_e32 v34, v67
	v_mov_b32_e32 v150, v68
	v_mov_b32_e32 v151, v36
	v_mov_b32_e32 v36, v69
	s_waitcnt lgkmcnt(7)
	v_mov_b32_e32 v148, v70
	s_waitcnt lgkmcnt(6)
	v_mov_b32_e32 v149, v38
	v_mov_b32_e32 v38, v71
	v_mov_b32_e32 v146, v72
	v_mov_b32_e32 v147, v40
	ds_read_b128 v[58:61], v107 offset:8304
	v_mov_b32_e32 v40, v73
	s_waitcnt lgkmcnt(6)
	v_mov_b32_e32 v72, v74
	s_waitcnt lgkmcnt(5)
	v_mov_b32_e32 v73, v42
	v_mov_b32_e32 v42, v75
	v_mov_b32_e32 v70, v76
	v_mov_b32_e32 v71, v44
	v_mov_b32_e32 v44, v77
	s_waitcnt lgkmcnt(4)
	v_mov_b32_e32 v68, v176
	s_waitcnt lgkmcnt(3)
	v_mov_b32_e32 v69, v46
	s_waitcnt vmcnt(30)
	v_pk_fma_f32 v[2:3], v[170:171], v[2:3], v[54:55] op_sel_hi:[0,1,1]
	v_fmac_f32_e32 v105, v170, v19
	s_waitcnt vmcnt(29)
	v_pk_fma_f32 v[2:3], v[168:169], v[172:173], v[2:3] op_sel_hi:[0,1,1]
	v_fmac_f32_e32 v105, v168, v20
	s_waitcnt vmcnt(28)
	v_pk_fma_f32 v[2:3], v[144:145], v[4:5], v[2:3] op_sel_hi:[0,1,1]
	v_fmac_f32_e32 v105, v144, v21
	s_waitcnt vmcnt(27)
	v_pk_fma_f32 v[2:3], v[142:143], v[164:165], v[2:3] op_sel_hi:[0,1,1]
	v_fmac_f32_e32 v105, v142, v14
	s_waitcnt vmcnt(26)
	v_pk_fma_f32 v[2:3], v[140:141], v[6:7], v[2:3] op_sel_hi:[0,1,1]
	v_fmac_f32_e32 v105, v140, v15
	s_waitcnt vmcnt(25)
	v_pk_fma_f32 v[2:3], v[138:139], v[162:163], v[2:3] op_sel_hi:[0,1,1]
	v_fmac_f32_e32 v105, v138, v16
	s_waitcnt vmcnt(24)
	v_pk_fma_f32 v[2:3], v[136:137], v[8:9], v[2:3] op_sel_hi:[0,1,1]
	v_fmac_f32_e32 v105, v136, v17
	s_waitcnt vmcnt(23)
	v_pk_fma_f32 v[2:3], v[134:135], v[160:161], v[2:3] op_sel_hi:[0,1,1]
	v_fmac_f32_e32 v105, v134, v10
	s_waitcnt vmcnt(22)
	v_pk_fma_f32 v[2:3], v[132:133], v[22:23], v[2:3] op_sel_hi:[0,1,1]
	v_fmac_f32_e32 v105, v132, v11
	s_waitcnt vmcnt(21)
	v_pk_fma_f32 v[2:3], v[130:131], v[158:159], v[2:3] op_sel_hi:[0,1,1]
	v_fmac_f32_e32 v105, v130, v12
	s_waitcnt vmcnt(20)
	v_pk_fma_f32 v[2:3], v[128:129], v[24:25], v[2:3] op_sel_hi:[0,1,1]
	v_fmac_f32_e32 v105, v128, v13
	s_waitcnt vmcnt(19)
	v_pk_fma_f32 v[2:3], v[126:127], v[156:157], v[2:3] op_sel_hi:[0,1,1]
	v_fmac_f32_e32 v105, v126, v30
	s_waitcnt vmcnt(18)
	v_pk_fma_f32 v[2:3], v[124:125], v[26:27], v[2:3] op_sel_hi:[0,1,1]
	v_fmac_f32_e32 v105, v124, v31
	s_waitcnt vmcnt(17)
	v_pk_fma_f32 v[2:3], v[122:123], v[154:155], v[2:3] op_sel_hi:[0,1,1]
	v_fmac_f32_e32 v105, v122, v32
	s_waitcnt vmcnt(16)
	v_pk_fma_f32 v[2:3], v[120:121], v[28:29], v[2:3] op_sel_hi:[0,1,1]
	v_fmac_f32_e32 v105, v120, v33
	s_waitcnt vmcnt(15)
	v_pk_fma_f32 v[2:3], v[118:119], v[152:153], v[2:3] op_sel_hi:[0,1,1]
	s_waitcnt lgkmcnt(2)
	v_fmac_f32_e32 v105, v118, v62
	s_waitcnt vmcnt(14)
	v_pk_fma_f32 v[2:3], v[116:117], v[34:35], v[2:3] op_sel_hi:[0,1,1]
	v_fmac_f32_e32 v105, v116, v63
	s_waitcnt vmcnt(13)
	v_pk_fma_f32 v[2:3], v[114:115], v[150:151], v[2:3] op_sel_hi:[0,1,1]
	v_fmac_f32_e32 v105, v114, v64
	ds_read_b128 v[54:57], v107 offset:8288
	s_waitcnt vmcnt(12)
	v_pk_fma_f32 v[2:3], v[112:113], v[36:37], v[2:3] op_sel_hi:[0,1,1]
	v_fmac_f32_e32 v105, v112, v65
	s_waitcnt vmcnt(11)
	v_pk_fma_f32 v[2:3], v[110:111], v[148:149], v[2:3] op_sel_hi:[0,1,1]
	s_waitcnt lgkmcnt(2)
	v_fmac_f32_e32 v105, v110, v50
	v_add_u32_e32 v107, 0x80, v107
	s_waitcnt vmcnt(10)
	v_pk_fma_f32 v[2:3], v[108:109], v[38:39], v[2:3] op_sel_hi:[0,1,1]
	v_fmac_f32_e32 v105, v108, v51
	s_waitcnt vmcnt(9)
	v_pk_fma_f32 v[2:3], v[106:107], v[146:147], v[2:3] op_sel_hi:[0,1,1]
	v_fmac_f32_e32 v105, v106, v52
	s_waitcnt vmcnt(8)
	v_pk_fma_f32 v[2:3], v[104:105], v[40:41], v[2:3] op_sel_hi:[0,1,1]
	v_fmac_f32_e32 v105, v104, v53
	s_waitcnt vmcnt(7)
	v_pk_fma_f32 v[2:3], v[102:103], v[72:73], v[2:3] op_sel_hi:[0,1,1]
	s_waitcnt lgkmcnt(0)
	v_fmac_f32_e32 v105, v102, v54
	s_waitcnt vmcnt(6)
	v_pk_fma_f32 v[2:3], v[100:101], v[42:43], v[2:3] op_sel_hi:[0,1,1]
	v_fmac_f32_e32 v105, v100, v55
	s_waitcnt vmcnt(5)
	v_pk_fma_f32 v[2:3], v[98:99], v[70:71], v[2:3] op_sel_hi:[0,1,1]
	v_fmac_f32_e32 v105, v98, v56
	s_waitcnt vmcnt(4)
	v_pk_fma_f32 v[2:3], v[96:97], v[44:45], v[2:3] op_sel_hi:[0,1,1]
	v_fmac_f32_e32 v105, v96, v57
	v_mov_b32_e32 v46, v177
	s_waitcnt vmcnt(3)
	v_pk_fma_f32 v[2:3], v[94:95], v[68:69], v[2:3] op_sel_hi:[0,1,1]
	v_fmac_f32_e32 v105, v94, v58
	v_mov_b32_e32 v66, v178
	v_mov_b32_e32 v67, v48
	s_add_u32 s38, s38, 0xc0000
	s_waitcnt vmcnt(2)
	v_pk_fma_f32 v[2:3], v[92:93], v[46:47], v[2:3] op_sel_hi:[0,1,1]
	v_fmac_f32_e32 v105, v92, v59
	v_mov_b32_e32 v48, v179
	s_addc_u32 s39, s39, 0
	s_waitcnt vmcnt(1)
	v_pk_fma_f32 v[2:3], v[90:91], v[66:67], v[2:3] op_sel_hi:[0,1,1]
	v_fmac_f32_e32 v105, v90, v60
	s_cmp_eq_u32 s38, 0x300000
	s_waitcnt vmcnt(0)
	v_pk_fma_f32 v[86:87], v[88:89], v[48:49], v[2:3] op_sel_hi:[0,1,1]
	v_fmac_f32_e32 v105, v88, v61
	s_cbranch_scc0 .LBB0_114
	s_movk_i32 s0, 0x180
	v_mul_lo_u32 v2, v82, s0
	v_add3_u32 v2, 0, v2, v80
	s_movk_i32 s0, 0x60
	v_add_u32_e32 v3, 0x3000, v2
	v_cmp_gt_i32_e32 vcc, s0, v99
	ds_write2_b32 v3, v86, v87 offset1:32
	ds_write_b32 v2, v105 offset:12544
	s_waitcnt lgkmcnt(0)
	s_barrier
	s_and_saveexec_b64 s[0:1], vcc
	s_cbranch_execz .LBB0_9
	s_mul_i32 s4, s2, 0x1800
	s_add_i32 s4, s4, s96
	v_or_b32_e32 v2, s4, v101
	v_ashrrev_i32_e32 v3, 31, v2
	v_lshl_add_u64 v[2:3], v[2:3], 2, s[68:69]
	global_load_dword v12, v[2:3], off
	v_add3_u32 v4, 0, v80, v103
	v_mad_u64_u32 v[2:3], s[4:5], s2, 3, v[82:83]
	v_add_u32_e32 v3, 0x3000, v4
	v_add_u32_e32 v5, 0x3200, v4
	v_add_u32_e32 v6, 0x3400, v4
	v_add_u32_e32 v8, 0x3800, v4
	s_movk_i32 s2, 0x1800
	v_mul_lo_u32 v10, v2, s2
	ds_read2_b32 v[2:3], v3 offset1:96
	ds_read2_b32 v[4:5], v5 offset0:64 offset1:160
	ds_read2_b32 v[6:7], v6 offset0:128 offset1:224
	ds_read2_b32 v[8:9], v8 offset0:64 offset1:160
	v_add_u32_e32 v10, s96, v10
	v_or_b32_e32 v10, v10, v101
	v_readlane_b32 s4, v242, 58
	v_ashrrev_i32_e32 v11, 31, v10
	v_readlane_b32 s5, v242, 59
	s_waitcnt vmcnt(0) lgkmcnt(3)
	v_add_f32_e32 v2, v12, v2
	v_add_f32_e32 v2, v2, v3
	s_waitcnt lgkmcnt(2)
	v_add_f32_e32 v2, v2, v4
	v_add_f32_e32 v2, v2, v5
	s_waitcnt lgkmcnt(1)
	v_add_f32_e32 v2, v2, v6
	v_add_f32_e32 v2, v2, v7
	s_waitcnt lgkmcnt(0)
	v_add_f32_e32 v2, v2, v8
	v_add_f32_e32 v4, v2, v9
	v_lshl_add_u64 v[2:3], v[10:11], 2, s[4:5]
	global_store_dword v[2:3], v4, off
	s_branch .LBB0_9
.LBB0_149:
	v_readlane_b32 s100, v242, 0
	s_movk_i32 s67, 0x80
	s_movk_i32 s66, 0x280
	s_sub_u32 s100, s100, 0x180
	s_waitcnt vmcnt(0) lgkmcnt(0)
	s_barrier
	v_readlane_b32 s0, v242, 42
	v_readlane_b32 s1, v242, 43
	v_readlane_b32 s4, v242, 3
	v_readlane_b32 s5, v242, 4
	v_lshrrev_b32_e32 v209, 6, v137
	v_and_b32_e32 v210, 63, v137
	s_sub_u32 s0, s0, 0x118
	s_subb_u32 s1, s1, 0
	v_lshrrev_b32_e32 v211, 3, v137
	v_and_b32_e32 v212, 7, v137
	v_mul_u32_u24_e32 v202, 65, v209
	v_mul_u32_u24_e32 v203, 0x208, v212
	v_add_u32_e32 v202, v202, v210
	v_add_u32_e32 v203, v203, v211
	v_lshlrev_b32_e32 v202, 2, v202
	v_lshlrev_b32_e32 v203, 2, v203
	v_lshlrev_b32_e32 v210, 2, v210
	v_lshlrev_b32_e32 v212, 4, v212
	v_add_u32_e32 v204, 0x400, v203
	v_add_u32_e32 v205, 0x80, v203
	v_add_u32_e32 v206, 0x480, v203
	s_cmp_ge_u32 s100, s66
	s_cbranch_scc1 .Lwc0_done
	s_cmpk_ge_u32 s100, 0x900
	s_cbranch_scc1 .Lwc0_t3_1
	s_cmpk_ge_u32 s100, 0x380
	s_cbranch_scc1 .Lwc0_t2_1
	s_cmpk_ge_u32 s100, 0x280
	s_cbranch_scc1 .Lwc0_t1_1
	s_movk_i32 s41, 0x78
	s_sub_u32 s99, s100, 0
	s_mul_i32 s44, s99, 0x66667
	s_lshr_b32 s44, s44, 24
	s_mul_i32 s36, s44, 40
	s_sub_u32 s99, s99, s36
	s_mul_i32 s38, s44, 0xa0000
	s_lshl_b32 s36, s99, 8
	s_add_u32 s38, s38, s36
	s_add_u32 s38, s38, 0x0
	s_lshl_b32 s36, s99, 6
	s_mov_b32 s32, 0x10000
	s_mul_i32 s36, s36, 0x800
	s_lshl_b32 s44, s44, 7
	s_add_u32 s36, s36, s44
	s_add_u32 s36, s36, 0x0
	s_mov_b32 s37, 0xa000
	s_movk_i32 s44, 0x800
	s_mov_b32 s99, 0x2800
	s_branch .Lwc0_tj_1
